# phase 0 Hyena filter: w3 of the layer staged once per workgroup in LDS via LDS-DMA and read with ds_read_b32 instead of re-streaming 128 KiB per item from L2; third-round filter items dealt to the les
# speedup vs baseline: 1.0493x; 1.0070x over previous
.LBB0_54:
	v_writelane_b32 v254, s54, 5
	s_cmpk_gt_i32 s33, 0x11ff
	v_mbcnt_lo_u32_b32 v224, -1, 0
	v_writelane_b32 v254, s55, 6
	s_cbranch_scc1 .LBB0_120
	v_add_u32_e32 v0, -1, v27
	v_and_b32_e32 v0, 15, v0
	v_cvt_f32_ubyte0_e32 v0, v0
	v_mul_f32_e32 v0, 0x416fff97, v0
	s_mov_b32 s4, 0x41700000
	v_div_scale_f32 v1, s[0:1], s4, s4, v0
	v_rcp_f32_e32 v2, v1
	s_mov_b32 s57, 0x437f0000
	s_load_dwordx8 s[16:23], s[30:31], 0x90
	s_load_dwordx4 s[24:27], s[30:31], 0xb0
	v_fma_f32 v3, -v1, v2, 1.0
	v_fmac_f32_e32 v2, v3, v2
	v_div_scale_f32 v3, vcc, v0, s4, v0
	v_mul_f32_e32 v4, v3, v2
	v_fma_f32 v5, -v1, v4, v3
	v_fmac_f32_e32 v4, v5, v2
	v_fma_f32 v1, -v1, v4, v3
	v_div_fmas_f32 v1, v1, v2, v4
	v_div_fixup_f32 v0, v1, s4, v0
	v_cvt_f32_ubyte0_e32 v1, v26
	v_mul_f32_e32 v2, 0x41447cbd, v1
	v_div_scale_f32 v3, s[0:1], s57, s57, v2
	v_rcp_f32_e32 v4, v3
	v_add_f32_e32 v18, 0x38d1b717, v0
	v_mov_b32_e32 v1, 0
	s_add_u32 s2, s28, 0x5100000
	v_fma_f32 v0, -v3, v4, 1.0
	v_fmac_f32_e32 v4, v0, v4
	v_div_scale_f32 v0, vcc, v2, s57, v2
	v_mul_f32_e32 v5, v0, v4
	v_fma_f32 v6, -v3, v5, v0
	v_fmac_f32_e32 v5, v6, v4
	v_fma_f32 v0, -v3, v5, v0
	v_or_b32_e32 v3, 64, v26
	v_cvt_f32_ubyte0_e32 v3, v3
	v_mul_f32_e32 v3, 0x41447cbd, v3
	v_div_scale_f32 v6, s[0:1], s57, s57, v3
	v_rcp_f32_e32 v7, v6
	v_div_fmas_f32 v0, v0, v4, v5
	v_div_fixup_f32 v0, v0, s57, v2
	v_sub_f32_e32 v19, 0xc0447cbd, v0
	v_fma_f32 v0, -v6, v7, 1.0
	v_fmac_f32_e32 v7, v0, v7
	v_div_scale_f32 v0, vcc, v3, s57, v3
	v_mul_f32_e32 v2, v0, v7
	v_fma_f32 v4, -v6, v2, v0
	v_fmac_f32_e32 v2, v4, v7
	v_or_b32_e32 v4, 0x80, v26
	v_cvt_f32_ubyte0_e32 v4, v4
	v_mul_f32_e32 v4, 0x41447cbd, v4
	v_div_scale_f32 v5, s[0:1], s57, s57, v4
	v_fma_f32 v0, -v6, v2, v0
	v_rcp_f32_e32 v6, v5
	v_div_fmas_f32 v0, v0, v7, v2
	v_div_fixup_f32 v0, v0, s57, v3
	v_sub_f32_e32 v20, 0xc0447cbd, v0
	v_fma_f32 v0, -v5, v6, 1.0
	v_fmac_f32_e32 v6, v0, v6
	v_div_scale_f32 v0, vcc, v4, s57, v4
	v_mul_f32_e32 v2, v0, v6
	v_fma_f32 v3, -v5, v2, v0
	v_fmac_f32_e32 v2, v3, v6
	v_or_b32_e32 v3, 0xc0, v26
	v_cvt_f32_ubyte0_e32 v3, v3
	v_mul_f32_e32 v3, 0x41447cbd, v3
	v_fma_f32 v0, -v5, v2, v0
	v_div_scale_f32 v5, s[0:1], s57, s57, v3
	v_rcp_f32_e32 v7, v5
	v_div_fmas_f32 v0, v0, v6, v2
	v_div_fixup_f32 v0, v0, s57, v4
	v_sub_f32_e32 v21, 0xc0447cbd, v0
	v_fma_f32 v0, -v5, v7, 1.0
	v_fmac_f32_e32 v7, v0, v7
	v_div_scale_f32 v0, vcc, v3, s57, v3
	v_mul_f32_e32 v2, v0, v7
	v_fma_f32 v4, -v5, v2, v0
	v_fmac_f32_e32 v2, v4, v7
	v_fma_f32 v0, -v5, v2, v0
	v_div_fmas_f32 v0, v0, v7, v2
	v_div_fixup_f32 v0, v0, s57, v3
	v_sub_f32_e32 v22, 0xc0447cbd, v0
	v_subrev_u32_e32 v0, 33, v26
	s_movk_i32 s0, 0xffdf
	v_cmp_lt_u32_e64 s[6:7], s0, v0
	v_lshlrev_b32_e32 v0, 2, v26
	s_waitcnt lgkmcnt(0)
	v_lshl_add_u64 v[2:3], s[16:17], 0, v[0:1]
	v_lshl_add_u64 v[4:5], s[20:21], 0, v[0:1]
	v_lshl_add_u64 v[6:7], s[24:25], 0, v[0:1]
	s_mov_b64 s[0:1], 0xa00
	v_mbcnt_hi_u32_b32 v0, -1, v224
	v_lshl_add_u64 v[2:3], v[2:3], 0, s[0:1]
	s_mov_b64 s[0:1], 0x700
	v_lshlrev_b32_e32 v32, 2, v0
	s_addc_u32 s56, s29, 0
	s_mov_b32 s35, 0
	v_cmp_eq_u32_e64 s[8:9], 0, v26
	v_cmp_lt_u32_e64 s[4:5], 16, v26
	v_lshl_add_u64 v[4:5], v[4:5], 0, s[0:1]
	s_mov_b32 s61, 0x44ffe000
	s_brev_b32 s62, 18
	s_mov_b32 s63, 0xfe5163ab
	s_mov_b32 s64, 0x3c439041
	s_mov_b32 s65, 0xdb629599
	s_mov_b32 s66, 0xf534ddc0
	s_mov_b32 s67, 0xfc2757d1
	s_mov_b32 s73, 0x4e441529
	s_mov_b32 s69, 0xa2f9836e
	s_mov_b32 s70, 0x3fc90fda
	s_mov_b32 s71, 0x3f22f983
	s_mov_b32 s72, 0xbfc90fda
	v_mov_b32_e32 v23, 0x3c0881c4
	v_mov_b32_e32 v25, 0xbab64f3b
	s_brev_b32 s74, 1
	s_mov_b32 s75, 0x7f800000
	s_mov_b64 s[20:21], 0xb00
	s_movk_i32 s76, 0x1f8
	s_mov_b64 s[24:25], 0x800
	s_movk_i32 s77, 0x1000
	s_mov_b32 s78, 0x3fb8aa3b
	s_mov_b32 s79, 0xc2ce8ed0
	s_mov_b32 s80, 0x42b17218
	s_mov_b64 s[36:37], 0x40000
	s_mov_b32 s81, 0x40000
	v_not_b32_e32 v28, 63
	v_not_b32_e32 v29, 31
	v_mov_b32_e32 v30, 0xffc00000
	v_mov_b32_e32 v31, 0x7fc00000
	v_and_b32_e32 v33, 0x100, v32
	v_mov_b32_e32 v34, 0x7f800000
	s_mov_b32 s101, -1
	s_branch .LBB0_57
.LBB0_56:
	s_add_i32 s33, s33, s68
	s_cmpk_lg_i32 s68, 0x800
	s_cbranch_scc1 .Lflt_chk
	s_sub_i32 s0, s33, 0x1000
	s_cmp_lt_u32 s0, 0x800
	s_cbranch_scc0 .Lflt_chk
	s_sub_i32 s33, 0x27ff, s33
.Lflt_chk:
	s_cmpk_gt_i32 s33, 0x11ff
	s_cbranch_scc1 .LBB0_120
.LBB0_57:
	s_mul_hi_i32 s0, s33, 0x38e38e39
	s_lshr_b32 s1, s0, 31
	s_ashr_i32 s0, s0, 9
	s_add_i32 s0, s0, s1
	s_cmpk_lg_i32 s68, 0x800
	s_cbranch_scc1 .Lflt_nostage
	s_cmp_eq_u32 s0, s101
	s_cbranch_scc1 .Lflt_nostage
	s_barrier
	s_load_dwordx2 s[10:11], s[30:31], 0xb0
	s_lshl_b32 s1, s0, 17
	v_mbcnt_lo_u32_b32 v101, -1, 0
	v_mbcnt_hi_u32_b32 v101, -1, v101
	v_lshlrev_b32_e32 v100, 4, v101
	v_lshlrev_b32_e32 v101, 2, v101
	s_waitcnt lgkmcnt(0)
	s_add_u32 s10, s10, s1
	s_addc_u32 s11, s11, 0
	s_lshl_b32 s1, s86, 8
	s_add_u32 s10, s10, s1
	s_addc_u32 s11, s11, 0
	s_add_i32 m0, s1, 0x0
	s_nop 0
	global_load_lds_dwordx4 v100, s[10:11]
	global_load_lds_dwordx4 v100, s[10:11] offset:1024
	global_load_lds_dwordx4 v100, s[10:11] offset:2048
	global_load_lds_dwordx4 v100, s[10:11] offset:3072
	s_add_i32 m0, s1, 0x1000
	s_add_u32 s10, s10, 0x1000
	s_addc_u32 s11, s11, 0
	global_load_lds_dwordx4 v100, s[10:11]
	global_load_lds_dwordx4 v100, s[10:11] offset:1024
	global_load_lds_dwordx4 v100, s[10:11] offset:2048
	global_load_lds_dwordx4 v100, s[10:11] offset:3072
	s_add_i32 m0, s1, 0x2000
	s_add_u32 s10, s10, 0x1000
	s_addc_u32 s11, s11, 0
	global_load_lds_dwordx4 v100, s[10:11]
	global_load_lds_dwordx4 v100, s[10:11] offset:1024
	global_load_lds_dwordx4 v100, s[10:11] offset:2048
	global_load_lds_dwordx4 v100, s[10:11] offset:3072
	s_add_i32 m0, s1, 0x3000
	s_add_u32 s10, s10, 0x1000
	s_addc_u32 s11, s11, 0
	global_load_lds_dwordx4 v100, s[10:11]
	global_load_lds_dwordx4 v100, s[10:11] offset:1024
	global_load_lds_dwordx4 v100, s[10:11] offset:2048
	global_load_lds_dwordx4 v100, s[10:11] offset:3072
	s_mov_b32 s101, s0
	s_waitcnt vmcnt(0)
	s_barrier
.Lflt_nostage:
	s_mul_i32 s1, s0, 0x900
	s_sub_i32 s38, s33, s1
	s_ashr_i32 s1, s0, 31
	s_mul_i32 s11, s0, 0x480000
	s_mul_hi_i32 s10, s0, 0x480000
	s_add_u32 s82, s2, s11
	s_addc_u32 s83, s56, s10
	s_lshl_b32 s10, s0, 6
	s_ashr_i32 s11, s10, 31
	s_lshl_b64 s[10:11], s[10:11], 2
	s_add_u32 s50, s18, s10
	s_addc_u32 s51, s19, s11
	s_lshl_b64 s[42:43], s[0:1], 14
	s_add_u32 s44, s22, s10
	s_mul_hi_i32 s49, s0, 0x2100
	s_mul_i32 s48, s0, 0x2100
	s_addc_u32 s45, s23, s11
	s_lshl_b64 s[40:41], s[0:1], 17
	s_lshl_b32 s0, s0, 7
	s_ashr_i32 s1, s0, 31
	s_lshl_b64 s[0:1], s[0:1], 2
	s_add_u32 s46, s26, s0
	s_addc_u32 s47, s27, s1
	s_cmpk_gt_i32 s38, 0xff
	s_mov_b64 s[0:1], -1
	s_cbranch_scc0 .LBB0_89
	s_add_i32 s0, s38, 0xffffff00
	v_cvt_f32_u32_e32 v0, s0
	v_div_scale_f32 v8, s[10:11], s61, s61, v0
	v_rcp_f32_e32 v9, v8
	v_div_scale_f32 v10, vcc, v0, s61, v0
	v_fma_f32 v11, -v8, v9, 1.0
	v_fmac_f32_e32 v9, v11, v9
	v_mul_f32_e32 v11, v10, v9
	v_fma_f32 v12, -v8, v11, v10
	v_fmac_f32_e32 v11, v12, v9
	v_fma_f32 v8, -v8, v11, v10
	v_div_fmas_f32 v8, v8, v9, v11
	v_div_fixup_f32 v35, v8, s61, v0
	v_cndmask_b32_e64 v10, 0, v35, s[8:9]
	s_and_saveexec_b64 s[52:53], s[6:7]
	s_cbranch_execz .LBB0_72
	v_mul_f32_e32 v0, 0x3b490fdb, v0
	v_mul_f32_e32 v8, v18, v0
	v_cmp_ngt_f32_e32 vcc, s62, v8
	s_and_saveexec_b64 s[10:11], s[4:5]
	s_xor_b64 s[54:55], exec, s[10:11]
	s_cbranch_execz .LBB0_65
	s_and_saveexec_b64 s[10:11], vcc
	s_xor_b64 s[58:59], exec, s[10:11]
	s_cbranch_execz .LBB0_62
	v_lshrrev_b32_e32 v0, 23, v8
	v_add_u32_e32 v0, 0xffffff88, v0
	v_cmp_lt_u32_e64 s[10:11], 63, v0
	s_nop 1
	v_cndmask_b32_e64 v9, 0, v28, s[10:11]
	v_add_u32_e32 v0, v9, v0
	v_cmp_lt_u32_e64 s[12:13], 31, v0
	s_nop 1
	v_cndmask_b32_e64 v9, 0, v29, s[12:13]
	v_add_u32_e32 v0, v9, v0
	v_cmp_lt_u32_e64 s[14:15], 31, v0
	s_nop 1
	v_cndmask_b32_e64 v9, 0, v29, s[14:15]
	v_add_u32_e32 v9, v9, v0
	v_and_b32_e32 v0, 0x7fffff, v8
	v_or_b32_e32 v40, 0x800000, v0
	v_mad_u64_u32 v[10:11], s[16:17], v40, s63, 0
	v_mov_b32_e32 v0, v11
	v_mad_u64_u32 v[12:13], s[16:17], v40, s64, v[0:1]
	v_mov_b32_e32 v0, v13
	v_mad_u64_u32 v[14:15], s[16:17], v40, s65, v[0:1]
	v_mov_b32_e32 v0, v15
	v_mad_u64_u32 v[16:17], s[16:17], v40, s66, v[0:1]
	v_mov_b32_e32 v0, v17
	v_mad_u64_u32 v[36:37], s[16:17], v40, s67, v[0:1]
	v_mov_b32_e32 v0, v37
	v_mad_u64_u32 v[38:39], s[16:17], v40, s73, v[0:1]
	v_mov_b32_e32 v0, v39
	v_mad_u64_u32 v[40:41], s[16:17], v40, s69, v[0:1]
	v_cndmask_b32_e64 v11, v38, v16, s[10:11]
	v_cndmask_b32_e64 v0, v40, v36, s[10:11]
	v_cndmask_b32_e64 v15, v41, v38, s[10:11]
	v_cndmask_b32_e64 v13, v0, v11, s[12:13]
	v_cndmask_b32_e64 v0, v15, v0, s[12:13]
	v_cndmask_b32_e64 v15, v36, v14, s[10:11]
	v_cndmask_b32_e64 v11, v11, v15, s[12:13]
	v_sub_u32_e32 v17, 32, v9
	v_cmp_eq_u32_e64 s[16:17], 0, v9
	v_cndmask_b32_e64 v9, v16, v12, s[10:11]
	v_cndmask_b32_e64 v0, v0, v13, s[14:15]
	v_cndmask_b32_e64 v13, v13, v11, s[14:15]
	v_cndmask_b32_e64 v12, v15, v9, s[12:13]
	v_alignbit_b32 v36, v0, v13, v17
	v_cndmask_b32_e64 v11, v11, v12, s[14:15]
	v_cndmask_b32_e64 v0, v36, v0, s[16:17]
	v_alignbit_b32 v15, v13, v11, v17
	v_cndmask_b32_e64 v10, v14, v10, s[10:11]
	v_cndmask_b32_e64 v13, v15, v13, s[16:17]
	v_bfe_u32 v36, v0, 29, 1
	v_cndmask_b32_e64 v9, v9, v10, s[12:13]
	v_alignbit_b32 v15, v0, v13, 30
	v_sub_u32_e32 v37, 0, v36
	v_cndmask_b32_e64 v9, v12, v9, s[14:15]
	v_xor_b32_e32 v15, v15, v37
	v_alignbit_b32 v10, v11, v9, v17
	v_cndmask_b32_e64 v10, v10, v11, s[16:17]
	v_ffbh_u32_e32 v12, v15
	v_alignbit_b32 v11, v13, v10, 30
	v_min_u32_e32 v12, 32, v12
	v_alignbit_b32 v9, v10, v9, 30
	v_xor_b32_e32 v11, v11, v37
	v_sub_u32_e32 v13, 31, v12
	v_xor_b32_e32 v9, v9, v37
	v_alignbit_b32 v14, v15, v11, v13
	v_alignbit_b32 v9, v11, v9, v13
	v_alignbit_b32 v10, v14, v9, 9
	v_ffbh_u32_e32 v11, v10
	v_min_u32_e32 v11, 32, v11
	v_lshrrev_b32_e32 v16, 29, v0
	v_not_b32_e32 v13, v11
	v_alignbit_b32 v9, v10, v9, v13
	v_lshlrev_b32_e32 v10, 31, v16
	v_or_b32_e32 v13, 0x33000000, v10
	v_add_lshl_u32 v11, v11, v12, 23
	v_lshrrev_b32_e32 v9, 9, v9
	v_sub_u32_e32 v11, v13, v11
	v_or_b32_e32 v10, 0.5, v10
	v_lshlrev_b32_e32 v12, 23, v12
	v_or_b32_e32 v9, v11, v9
	v_lshrrev_b32_e32 v11, 9, v14
	v_sub_u32_e32 v10, v10, v12
	v_or_b32_e32 v10, v11, v10
	v_mul_f32_e32 v11, 0x3fc90fda, v10
	v_fma_f32 v12, v10, s70, -v11
	v_fmac_f32_e32 v12, 0x33a22168, v10
	v_fmac_f32_e32 v12, 0x3fc90fda, v9
	v_lshrrev_b32_e32 v0, 30, v0
	v_add_f32_e32 v9, v11, v12
	v_add_u32_e32 v0, v36, v0

.LBB0_82:
	s_andn2_saveexec_b64 s[10:11], s[16:17]
	v_mul_f32_e64 v10, |v8|, s71
	v_rndne_f32_e32 v12, v10
	v_cvt_i32_f32_e32 v10, v12
	v_fma_f32 v11, v12, s72, |v8|
	v_fmac_f32_e32 v11, 0xb3a22168, v12
	v_fmac_f32_e32 v11, 0xa7c234c4, v12
	s_or_b64 exec, exec, s[10:11]
	v_mul_f32_e32 v12, v11, v11
	v_fmamk_f32 v13, v12, 0xb94c1982, v23
	v_fmaak_f32 v13, v12, v13, 0xbe2aaa9d
	v_mul_f32_e32 v13, v12, v13
	v_fmac_f32_e32 v11, v11, v13
	v_fmamk_f32 v13, v12, 0x37d75334, v25
	v_fmaak_f32 v13, v12, v13, 0x3d2aabf7
	v_fmaak_f32 v13, v12, v13, 0xbf000004
	v_fma_f32 v12, v12, v13, 1.0
	v_and_b32_e32 v13, 1, v10
	v_lshlrev_b32_e32 v10, 30, v10
	v_cmp_eq_u32_e32 vcc, 0, v13
	v_and_b32_e32 v10, 0x80000000, v10
	v_xor_b32_e32 v9, v9, v8
	v_cndmask_b32_e32 v11, v12, v11, vcc
	v_xor_b32_e32 v9, v9, v10
	v_xor_b32_e32 v9, v9, v11
	v_cmp_class_f32_e64 vcc, v8, s76
	v_mov_b32_e32 v8, 0
	v_lshl_add_u64 v[16:17], v[6:7], 0, s[40:41]
	v_cndmask_b32_e32 v36, v31, v9, vcc
	s_mov_b64 s[10:11], 0
	v_mov_b32_e32 v37, v33
	v_mov_b32_e32 v9, v8
	v_mov_b32_e32 v14, v8
	v_mov_b32_e32 v15, v8
	v_mov_b32_e32 v12, v8
	v_mov_b32_e32 v13, v8
	v_mov_b32_e32 v10, v8
	v_mov_b32_e32 v11, v8
	s_cmpk_lg_i32 s68, 0x800
	s_cbranch_scc1 .LBB0_85
.Lflt_l3a:
	v_add_u32_e32 v102, s10, v101
	ds_bpermute_b32 v38, v37, v36
	ds_bpermute_b32 v72, v37, v36 offset:4
	ds_bpermute_b32 v74, v37, v36 offset:8
	ds_bpermute_b32 v76, v37, v36 offset:12
	ds_read_b32 v40, v102
	ds_read_b32 v41, v102 offset:256
	ds_read_b32 v42, v102 offset:512
	ds_read_b32 v43, v102 offset:768
	ds_read_b32 v44, v102 offset:1024
	ds_read_b32 v45, v102 offset:1280
	ds_read_b32 v46, v102 offset:1536
	ds_read_b32 v47, v102 offset:1792
	ds_read_b32 v48, v102 offset:2048
	ds_read_b32 v49, v102 offset:2304
	ds_read_b32 v50, v102 offset:2560
	ds_read_b32 v51, v102 offset:2816
	ds_read_b32 v52, v102 offset:3072
	ds_read_b32 v53, v102 offset:3328
	ds_read_b32 v54, v102 offset:3584
	ds_read_b32 v55, v102 offset:3840
	ds_read_b32 v56, v102 offset:4096
	ds_read_b32 v57, v102 offset:4352
	ds_read_b32 v58, v102 offset:4608
	ds_read_b32 v59, v102 offset:4864
	ds_read_b32 v60, v102 offset:5120
	ds_read_b32 v61, v102 offset:5376
	ds_read_b32 v62, v102 offset:5632
	ds_read_b32 v63, v102 offset:5888
	ds_read_b32 v64, v102 offset:6144
	ds_read_b32 v65, v102 offset:6400
	ds_read_b32 v66, v102 offset:6656
	ds_read_b32 v67, v102 offset:6912
	ds_read_b32 v68, v102 offset:7168
	ds_read_b32 v69, v102 offset:7424
	ds_read_b32 v70, v102 offset:7680
	ds_read_b32 v71, v102 offset:7936
	s_add_u32 s10, s10, 0x2000
	s_addc_u32 s11, s11, 0
	v_add_u32_e32 v37, 16, v37
	s_cmp_eq_u32 s10, 0x20000
	s_waitcnt lgkmcnt(15)
	v_pk_fma_f32 v[14:15], v[40:41], v[38:39], v[14:15] op_sel_hi:[1,0,1]
	v_pk_fma_f32 v[12:13], v[42:43], v[38:39], v[12:13] op_sel_hi:[1,0,1]
	v_pk_fma_f32 v[10:11], v[44:45], v[38:39], v[10:11] op_sel_hi:[1,0,1]
	v_pk_fma_f32 v[8:9], v[46:47], v[38:39], v[8:9] op_sel_hi:[1,0,1]
	v_pk_fma_f32 v[14:15], v[48:49], v[72:73], v[14:15] op_sel_hi:[1,0,1]
	v_pk_fma_f32 v[12:13], v[50:51], v[72:73], v[12:13] op_sel_hi:[1,0,1]
	v_pk_fma_f32 v[10:11], v[52:53], v[72:73], v[10:11] op_sel_hi:[1,0,1]
	v_pk_fma_f32 v[8:9], v[54:55], v[72:73], v[8:9] op_sel_hi:[1,0,1]
	s_waitcnt lgkmcnt(7)
	v_pk_fma_f32 v[14:15], v[56:57], v[74:75], v[14:15] op_sel_hi:[1,0,1]
	v_pk_fma_f32 v[12:13], v[58:59], v[74:75], v[12:13] op_sel_hi:[1,0,1]
	v_pk_fma_f32 v[10:11], v[60:61], v[74:75], v[10:11] op_sel_hi:[1,0,1]
	v_pk_fma_f32 v[8:9], v[62:63], v[74:75], v[8:9] op_sel_hi:[1,0,1]
	s_waitcnt lgkmcnt(0)
	v_pk_fma_f32 v[14:15], v[64:65], v[76:77], v[14:15] op_sel_hi:[1,0,1]
	v_pk_fma_f32 v[12:13], v[66:67], v[76:77], v[12:13] op_sel_hi:[1,0,1]
	v_pk_fma_f32 v[10:11], v[68:69], v[76:77], v[10:11] op_sel_hi:[1,0,1]
	v_pk_fma_f32 v[8:9], v[70:71], v[76:77], v[8:9] op_sel_hi:[1,0,1]
	s_cbranch_scc0 .Lflt_l3a
	s_branch .Lflt_l3a_done

.Lflt_l3a_done:
	v_mul_f32_e64 v16, |v19|, -v35
	v_mul_f32_e32 v17, 0x3fb8aa3b, v16
	v_fma_f32 v36, v16, s78, -v17
	v_rndne_f32_e32 v37, v17
	v_fmac_f32_e32 v36, 0x32a5705f, v16
	v_sub_f32_e32 v17, v17, v37
	v_add_f32_e32 v17, v17, v36
	v_exp_f32_e32 v17, v17
	v_cvt_i32_f32_e32 v36, v37
	s_add_u32 s1, s82, 0x80000
	s_addc_u32 s10, s83, 0
	s_add_i32 s34, s38, 0x700
	v_ldexp_f32 v17, v17, v36
	v_mul_f32_e64 v36, |v20|, -v35
	v_mul_f32_e32 v37, 0x3fb8aa3b, v36
	v_fma_f32 v38, v36, s78, -v37
	v_rndne_f32_e32 v39, v37
	v_fmac_f32_e32 v38, 0x32a5705f, v36
	v_sub_f32_e32 v37, v37, v39
	v_add_f32_e32 v37, v37, v38
	v_cmp_ngt_f32_e32 vcc, s79, v16
	v_exp_f32_e32 v37, v37
	v_cvt_i32_f32_e32 v38, v39
	s_lshl_b64 s[12:13], s[34:35], 10
	v_cndmask_b32_e32 v17, 0, v17, vcc
	v_cmp_nlt_f32_e32 vcc, s80, v16
	s_add_u32 s12, s1, s12
	s_addc_u32 s13, s10, s13
	v_cndmask_b32_e32 v16, v34, v17, vcc
	v_mul_f32_e32 v14, v16, v14
	v_mul_f32_e64 v17, |v21|, -v35
	global_store_dword v0, v14, s[12:13]
	v_ldexp_f32 v14, v37, v38
	v_mul_f32_e32 v37, 0x3fb8aa3b, v17
	v_fma_f32 v38, v17, s78, -v37
	v_rndne_f32_e32 v39, v37
	v_fmac_f32_e32 v38, 0x32a5705f, v17
	v_sub_f32_e32 v37, v37, v39
	v_add_f32_e32 v37, v37, v38
	v_cmp_ngt_f32_e32 vcc, s79, v36
	v_exp_f32_e32 v37, v37
	v_cvt_i32_f32_e32 v38, v39
	v_cndmask_b32_e32 v14, 0, v14, vcc
	v_cmp_nlt_f32_e32 vcc, s80, v36
	v_mul_f32_e64 v35, |v22|, -v35
	v_mul_f32_e32 v36, 0x3fb8aa3b, v35
	v_cndmask_b32_e32 v14, v34, v14, vcc
	v_mul_f32_e32 v15, v14, v15
	global_store_dword v0, v15, s[12:13] offset:256
	v_ldexp_f32 v15, v37, v38
	v_fma_f32 v37, v35, s78, -v36
	v_rndne_f32_e32 v38, v36
	v_fmac_f32_e32 v37, 0x32a5705f, v35
	v_sub_f32_e32 v36, v36, v38
	v_add_f32_e32 v36, v36, v37
	v_cmp_ngt_f32_e32 vcc, s79, v17
	v_exp_f32_e32 v36, v36
	v_cvt_i32_f32_e32 v37, v38
	v_cndmask_b32_e32 v15, 0, v15, vcc
	v_cmp_nlt_f32_e32 vcc, s80, v17
	s_cmp_lg_u32 s0, 0
	s_nop 0
	v_cndmask_b32_e32 v15, v34, v15, vcc
	v_mul_f32_e32 v12, v15, v12
	global_store_dword v0, v12, s[12:13] offset:512
	v_ldexp_f32 v12, v36, v37
	v_cmp_ngt_f32_e32 vcc, s79, v35
	s_nop 1
	v_cndmask_b32_e32 v12, 0, v12, vcc
	v_cmp_nlt_f32_e32 vcc, s80, v35
	s_nop 1
	v_cndmask_b32_e32 v12, v34, v12, vcc
	v_mul_f32_e32 v13, v12, v13
	global_store_dword v0, v13, s[12:13] offset:768
	s_cbranch_scc0 .LBB0_88
	s_lshl_b32 s0, s38, 10
	s_sub_i32 s0, 0x240000, s0
	s_add_u32 s0, s1, s0
	s_addc_u32 s1, s10, 0
	v_mul_f32_e32 v10, v16, v10
	v_mul_f32_e32 v8, v15, v8
	v_mul_f32_e32 v11, v14, v11
	global_store_dword v0, v10, s[0:1]
	global_store_dword v0, v11, s[0:1] offset:256
	v_mul_f32_e32 v9, v12, v9
	global_store_dword v0, v8, s[0:1] offset:512
	global_store_dword v0, v9, s[0:1] offset:768

.LBB0_114:
	s_andn2_saveexec_b64 s[10:11], s[16:17]
	v_mul_f32_e64 v10, |v8|, s71
	v_rndne_f32_e32 v12, v10
	v_cvt_i32_f32_e32 v10, v12
	v_fma_f32 v11, v12, s72, |v8|
	v_fmac_f32_e32 v11, 0xb3a22168, v12
	v_fmac_f32_e32 v11, 0xa7c234c4, v12
	s_or_b64 exec, exec, s[10:11]
	v_mul_f32_e32 v12, v11, v11
	v_fmamk_f32 v13, v12, 0xb94c1982, v23
	v_fmaak_f32 v13, v12, v13, 0xbe2aaa9d
	v_mul_f32_e32 v13, v12, v13
	v_fmac_f32_e32 v11, v11, v13
	v_fmamk_f32 v13, v12, 0x37d75334, v25
	v_fmaak_f32 v13, v12, v13, 0x3d2aabf7
	v_fmaak_f32 v13, v12, v13, 0xbf000004
	v_fma_f32 v12, v12, v13, 1.0
	v_and_b32_e32 v13, 1, v10
	v_lshlrev_b32_e32 v10, 30, v10
	v_cmp_eq_u32_e32 vcc, 0, v13
	v_and_b32_e32 v10, 0x80000000, v10
	v_xor_b32_e32 v9, v9, v8
	v_cndmask_b32_e32 v11, v12, v11, vcc
	v_xor_b32_e32 v9, v9, v10
	v_xor_b32_e32 v9, v9, v11
	v_cmp_class_f32_e64 vcc, v8, s76
	v_mov_b32_e32 v8, 0
	v_lshl_add_u64 v[16:17], v[6:7], 0, s[40:41]
	v_cndmask_b32_e32 v37, v31, v9, vcc
	s_mov_b64 s[10:11], 0
	v_mov_b32_e32 v9, v8
	v_mov_b32_e32 v14, v8
	v_mov_b32_e32 v15, v8
	v_mov_b32_e32 v12, v8
	v_mov_b32_e32 v13, v8
	v_mov_b32_e32 v10, v8
	v_mov_b32_e32 v11, v8
	s_cmpk_lg_i32 s68, 0x800
	s_cbranch_scc1 .LBB0_117
.Lflt_l3b:
	v_add_u32_e32 v102, s10, v101
	ds_bpermute_b32 v38, v36, v37
	ds_bpermute_b32 v72, v36, v37 offset:4
	ds_bpermute_b32 v74, v36, v37 offset:8
	ds_bpermute_b32 v76, v36, v37 offset:12
	ds_read_b32 v40, v102
	ds_read_b32 v41, v102 offset:256
	ds_read_b32 v42, v102 offset:512
	ds_read_b32 v43, v102 offset:768
	ds_read_b32 v44, v102 offset:1024
	ds_read_b32 v45, v102 offset:1280
	ds_read_b32 v46, v102 offset:1536
	ds_read_b32 v47, v102 offset:1792
	ds_read_b32 v48, v102 offset:2048
	ds_read_b32 v49, v102 offset:2304
	ds_read_b32 v50, v102 offset:2560
	ds_read_b32 v51, v102 offset:2816
	ds_read_b32 v52, v102 offset:3072
	ds_read_b32 v53, v102 offset:3328
	ds_read_b32 v54, v102 offset:3584
	ds_read_b32 v55, v102 offset:3840
	ds_read_b32 v56, v102 offset:4096
	ds_read_b32 v57, v102 offset:4352
	ds_read_b32 v58, v102 offset:4608
	ds_read_b32 v59, v102 offset:4864
	ds_read_b32 v60, v102 offset:5120
	ds_read_b32 v61, v102 offset:5376
	ds_read_b32 v62, v102 offset:5632
	ds_read_b32 v63, v102 offset:5888
	ds_read_b32 v64, v102 offset:6144
	ds_read_b32 v65, v102 offset:6400
	ds_read_b32 v66, v102 offset:6656
	ds_read_b32 v67, v102 offset:6912
	ds_read_b32 v68, v102 offset:7168
	ds_read_b32 v69, v102 offset:7424
	ds_read_b32 v70, v102 offset:7680
	ds_read_b32 v71, v102 offset:7936
	s_add_u32 s10, s10, 0x2000
	s_addc_u32 s11, s11, 0
	v_add_u32_e32 v36, 16, v36
	s_cmp_eq_u32 s10, 0x20000
	s_waitcnt lgkmcnt(15)
	v_pk_fma_f32 v[14:15], v[40:41], v[38:39], v[14:15] op_sel_hi:[1,0,1]
	v_pk_fma_f32 v[12:13], v[42:43], v[38:39], v[12:13] op_sel_hi:[1,0,1]
	v_pk_fma_f32 v[10:11], v[44:45], v[38:39], v[10:11] op_sel_hi:[1,0,1]
	v_pk_fma_f32 v[8:9], v[46:47], v[38:39], v[8:9] op_sel_hi:[1,0,1]
	v_pk_fma_f32 v[14:15], v[48:49], v[72:73], v[14:15] op_sel_hi:[1,0,1]
	v_pk_fma_f32 v[12:13], v[50:51], v[72:73], v[12:13] op_sel_hi:[1,0,1]
	v_pk_fma_f32 v[10:11], v[52:53], v[72:73], v[10:11] op_sel_hi:[1,0,1]
	v_pk_fma_f32 v[8:9], v[54:55], v[72:73], v[8:9] op_sel_hi:[1,0,1]
	s_waitcnt lgkmcnt(7)
	v_pk_fma_f32 v[14:15], v[56:57], v[74:75], v[14:15] op_sel_hi:[1,0,1]
	v_pk_fma_f32 v[12:13], v[58:59], v[74:75], v[12:13] op_sel_hi:[1,0,1]
	v_pk_fma_f32 v[10:11], v[60:61], v[74:75], v[10:11] op_sel_hi:[1,0,1]
	v_pk_fma_f32 v[8:9], v[62:63], v[74:75], v[8:9] op_sel_hi:[1,0,1]
	s_waitcnt lgkmcnt(0)
	v_pk_fma_f32 v[14:15], v[64:65], v[76:77], v[14:15] op_sel_hi:[1,0,1]
	v_pk_fma_f32 v[12:13], v[66:67], v[76:77], v[12:13] op_sel_hi:[1,0,1]
	v_pk_fma_f32 v[10:11], v[68:69], v[76:77], v[10:11] op_sel_hi:[1,0,1]
	v_pk_fma_f32 v[8:9], v[70:71], v[76:77], v[8:9] op_sel_hi:[1,0,1]
	s_cbranch_scc0 .Lflt_l3b
	s_branch .Lflt_l3b_done

.Lflt_l3b_done:
	v_mul_f32_e64 v16, |v19|, -v35
	v_mul_f32_e32 v17, 0x3fb8aa3b, v16
	v_fma_f32 v36, v16, s78, -v17
	v_rndne_f32_e32 v37, v17
	v_fmac_f32_e32 v36, 0x32a5705f, v16
	v_sub_f32_e32 v17, v17, v37
	v_add_f32_e32 v17, v17, v36
	v_exp_f32_e32 v17, v17
	v_cvt_i32_f32_e32 v36, v37
	v_cmp_ngt_f32_e32 vcc, s79, v16
	s_ashr_i32 s39, s38, 31
	s_lshl_b64 s[0:1], s[38:39], 10
	v_ldexp_f32 v17, v17, v36
	v_cndmask_b32_e32 v17, 0, v17, vcc
	v_cmp_nlt_f32_e32 vcc, s80, v16
	s_add_u32 s0, s82, s0
	s_addc_u32 s1, s83, s1
	v_cndmask_b32_e32 v16, v34, v17, vcc
	v_mul_f32_e64 v17, |v20|, -v35
	v_mul_f32_e32 v40, 0x3fb8aa3b, v17
	v_fma_f32 v41, v17, s78, -v40
	v_rndne_f32_e32 v42, v40
	v_fmac_f32_e32 v41, 0x32a5705f, v17
	v_sub_f32_e32 v40, v40, v42
	v_lshl_add_u64 v[36:37], s[0:1], 0, v[0:1]
	v_add_f32_e32 v40, v40, v41
	v_lshl_add_u64 v[38:39], v[36:37], 0, s[36:37]
	v_exp_f32_e32 v40, v40
	v_cvt_i32_f32_e32 v41, v42
	v_add_co_u32_e32 v36, vcc, s81, v36
	v_mul_f32_e32 v14, v16, v14
	s_nop 0
	v_addc_co_u32_e32 v37, vcc, 0, v37, vcc
	global_store_dword v[36:37], v14, off
	v_mul_f32_e64 v36, |v21|, -v35
	v_mul_f32_e32 v37, 0x3fb8aa3b, v36
	v_ldexp_f32 v14, v40, v41
	v_fma_f32 v40, v36, s78, -v37
	v_rndne_f32_e32 v41, v37
	v_fmac_f32_e32 v40, 0x32a5705f, v36
	v_sub_f32_e32 v37, v37, v41
	v_add_f32_e32 v37, v37, v40
	v_cmp_ngt_f32_e32 vcc, s79, v17
	v_exp_f32_e32 v37, v37
	v_cvt_i32_f32_e32 v40, v41
	v_cndmask_b32_e32 v14, 0, v14, vcc
	v_cmp_nlt_f32_e32 vcc, s80, v17
	v_mul_f32_e64 v17, |v22|, -v35
	v_mul_f32_e32 v35, 0x3fb8aa3b, v17
	v_cndmask_b32_e32 v14, v34, v14, vcc
	v_mul_f32_e32 v15, v14, v15
	global_store_dword v[38:39], v15, off offset:256
	v_ldexp_f32 v15, v37, v40
	v_fma_f32 v37, v17, s78, -v35
	v_rndne_f32_e32 v40, v35
	v_fmac_f32_e32 v37, 0x32a5705f, v17
	v_sub_f32_e32 v35, v35, v40
	v_add_f32_e32 v35, v35, v37
	v_cmp_ngt_f32_e32 vcc, s79, v36
	v_exp_f32_e32 v35, v35
	v_cvt_i32_f32_e32 v37, v40
	v_cndmask_b32_e32 v15, 0, v15, vcc
	v_cmp_nlt_f32_e32 vcc, s80, v36
	s_cmp_gt_i32 s38, 0
	s_nop 0
	v_cndmask_b32_e32 v15, v34, v15, vcc
	v_mul_f32_e32 v12, v15, v12
	global_store_dword v[38:39], v12, off offset:512
	v_ldexp_f32 v12, v35, v37
	v_cmp_ngt_f32_e32 vcc, s79, v17
	s_nop 1
	v_cndmask_b32_e32 v12, 0, v12, vcc
	v_cmp_nlt_f32_e32 vcc, s80, v17
	s_nop 1
	v_cndmask_b32_e32 v12, v34, v12, vcc
	v_mul_f32_e32 v13, v12, v13
	global_store_dword v[38:39], v13, off offset:768
	s_cbranch_scc0 .LBB0_56
	s_lshl_b32 s0, s38, 10
	s_sub_i32 s0, 0x40000, s0
	s_add_u32 s0, s82, s0
	s_addc_u32 s1, s83, 0
	v_mul_f32_e32 v10, v16, v10
	v_mul_f32_e32 v8, v15, v8
	v_mul_f32_e32 v11, v14, v11
	global_store_dword v0, v10, s[0:1]
	global_store_dword v0, v11, s[0:1] offset:256
	v_mul_f32_e32 v9, v12, v9
	global_store_dword v0, v8, s[0:1] offset:512
	global_store_dword v0, v9, s[0:1] offset:768
	s_branch .LBB0_56

	.amdhsa_kernel _Z8mega_fwd6Params
		.amdhsa_group_segment_fixed_size 0
		.amdhsa_private_segment_fixed_size 0
		.amdhsa_kernarg_size 520
		.amdhsa_user_sgpr_count 2
		.amdhsa_user_sgpr_dispatch_ptr 0
		.amdhsa_user_sgpr_queue_ptr 0
		.amdhsa_user_sgpr_kernarg_segment_ptr 1
		.amdhsa_user_sgpr_dispatch_id 0
		.amdhsa_user_sgpr_kernarg_preload_length 0
		.amdhsa_user_sgpr_kernarg_preload_offset 0
		.amdhsa_user_sgpr_private_segment_size 0
		.amdhsa_uses_dynamic_stack 0
		.amdhsa_enable_private_segment 0
		.amdhsa_system_sgpr_workgroup_id_x 1
		.amdhsa_system_sgpr_workgroup_id_y 0
		.amdhsa_system_sgpr_workgroup_id_z 0
		.amdhsa_system_sgpr_workgroup_info 0
		.amdhsa_system_vgpr_workitem_id 2
		.amdhsa_next_free_vgpr 256
		.amdhsa_next_free_sgpr 102
		.amdhsa_accum_offset 256
		.amdhsa_reserve_vcc 1
		.amdhsa_float_round_mode_32 0
		.amdhsa_float_round_mode_16_64 0
		.amdhsa_float_denorm_mode_32 3
		.amdhsa_float_denorm_mode_16_64 3
		.amdhsa_dx10_clamp 1
		.amdhsa_ieee_mode 1
		.amdhsa_fp16_overflow 0
		.amdhsa_tg_split 0
		.amdhsa_exception_fp_ieee_invalid_op 0
		.amdhsa_exception_fp_denorm_src 0
		.amdhsa_exception_fp_ieee_div_zero 0
		.amdhsa_exception_fp_ieee_overflow 0
		.amdhsa_exception_fp_ieee_underflow 0
		.amdhsa_exception_fp_ieee_inexact 0
		.amdhsa_exception_int_div_zero 0
	.end_amdhsa_kernel

amdhsa.kernels:
  - .agpr_count:     0
    .args:
      - .offset:         0
        .size:           264
        .value_kind:     by_value
      - .offset:         264
        .size:           4
        .value_kind:     hidden_block_count_x
      - .offset:         268
        .size:           4
        .value_kind:     hidden_block_count_y
      - .offset:         272
        .size:           4
        .value_kind:     hidden_block_count_z
      - .offset:         276
        .size:           2
        .value_kind:     hidden_group_size_x
      - .offset:         278
        .size:           2
        .value_kind:     hidden_group_size_y
      - .offset:         280
        .size:           2
        .value_kind:     hidden_group_size_z
      - .offset:         282
        .size:           2
        .value_kind:     hidden_remainder_x
      - .offset:         284
        .size:           2
        .value_kind:     hidden_remainder_y
      - .offset:         286
        .size:           2
        .value_kind:     hidden_remainder_z
      - .offset:         304
        .size:           8
        .value_kind:     hidden_global_offset_x
      - .offset:         312
        .size:           8
        .value_kind:     hidden_global_offset_y
      - .offset:         320
        .size:           8
        .value_kind:     hidden_global_offset_z
      - .offset:         328
        .size:           2
        .value_kind:     hidden_grid_dims
      - .offset:         352
        .size:           8
        .value_kind:     hidden_multigrid_sync_arg
      - .offset:         384
        .size:           4
        .value_kind:     hidden_dynamic_lds_size
    .group_segment_fixed_size: 0
    .kernarg_segment_align: 8
    .kernarg_segment_size: 520
    .language:       OpenCL C
    .language_version:
      - 2
      - 0
    .max_flat_workgroup_size: 512
    .name:           _Z8mega_fwd6Params
    .private_segment_fixed_size: 0
    .sgpr_count:     108
    .sgpr_spill_count: 112
    .symbol:         _Z8mega_fwd6Params.kd
    .uniform_work_group_size: 1
    .uses_dynamic_stack: false
    .vgpr_count:     256
    .vgpr_spill_count: 0
    .wavefront_size: 64
